# v39
# speedup vs baseline: 1.0124x; 1.0124x over previous
.LBB0_71:
	s_ashr_i32 s2, s2, 3
	s_add_i32 s2, s11, s2
	s_ashr_i32 s8, s2, 31
	s_lshr_b32 s8, s8, 29
	s_add_i32 s8, s2, s8
	s_and_b32 s9, s8, 0xfff8
	s_sub_i32 s2, s2, s9
	s_bfe_i32 s9, s2, 0x80000
	s_bfe_u32 s9, s9, 0x2000d
	s_add_i32 s9, s2, s9
	s_bfe_i32 s10, s9, 0x80000
	s_and_b32 s9, s9, 0xfc
	s_sub_i32 s2, s2, s9
	s_sext_i32_i8 s2, s2
	s_lshl_b32 s8, s8, 7
	s_sext_i32_i16 s10, s10
	s_and_b32 s8, s8, 0xfffffc00
	s_lshl_b32 s2, s2, 8
	s_add_i32 s12, s2, s8
	s_lshl_b32 s2, s10, 6
	s_and_b32 s14, s2, 0xffffff00
	s_ashr_i32 s13, s12, 31
	s_ashr_i32 s15, s14, 31
	s_lshl_b64 s[8:9], s[12:13], 10
	s_lshl_b64 s[10:11], s[14:15], 10
	s_add_u32 s64, s6, s8
	s_addc_u32 s2, s7, s9
	s_add_u32 s8, s18, s10
	s_waitcnt vmcnt(0)
	s_addc_u32 s9, s19, s11
	s_and_b32 s65, s2, 0xffff
	s_and_b32 s9, s9, 0xffff
	s_mov_b32 s13, 0
	s_mov_b32 s15, 0x30080
	s_waitcnt lgkmcnt(0)
	s_waitcnt vmcnt(0)
	s_barrier
	s_branch .LBB0_73
.LBB0_73:
	s_cmp_eq_u32 s15, 0x30400
	s_mov_b32 s2, 0x10000
	s_and_b32 s2, s13, 0x10000
	s_xor_b32 s10, s2, 0x10000
	s_add_i32 s16, s21, s10
	s_add_i32 s17, s15, 0xfffd0000
	s_add_i32 s30, s16, 0x8000
	s_mov_b32 s10, s66
	s_mov_b32 s11, s67
	s_waitcnt lgkmcnt(0)
	v_add_u32_e32 v228, s2, v138
	v_add_u32_e32 v229, s2, v136
	ds_read_b128 v[132:135], v229 offset:0
	ds_read_b128 v[140:143], v229 offset:0x800
	ds_read_b128 v[144:147], v229 offset:0x1000
	ds_read_b128 v[148:151], v229 offset:0x1800
	ds_read_b128 v[152:155], v228 offset:0
	ds_read_b128 v[156:159], v228 offset:0x800
	s_setprio 1
	s_mov_b32 m0, s16
	s_nop 0
	buffer_load_dwordx4 v131, s[64:67], s17 offen lds
	s_mov_b32 m0, s30
	s_nop 0
	buffer_load_dwordx4 v131, s[8:11], s17 offen lds
	s_add_i32 m0, s16, 0x2000
	s_add_i32 s17, s15, 0xfffe0000
	buffer_load_dwordx4 v131, s[64:67], s17 offen lds
	s_add_i32 m0, s16, 0xa000
	s_nop 0
	buffer_load_dwordx4 v131, s[8:11], s17 offen lds
	ds_read_b128 v[160:163], v228 offset:0x1000
	v_xor_b32_e32 v176, 64, v228
	s_waitcnt lgkmcnt(2)
	v_mfma_f32_16x16x32_bf16 v[126:129], v[152:155], v[132:135], 0
	v_mfma_f32_16x16x32_bf16 v[122:125], v[152:155], v[140:143], 0
	v_mfma_f32_16x16x32_bf16 v[118:121], v[152:155], v[144:147], 0
	v_mfma_f32_16x16x32_bf16 v[114:117], v[152:155], v[148:151], 0
	s_add_i32 m0, s16, 0x4000
	s_add_i32 s17, s15, 0xffff0000
	buffer_load_dwordx4 v131, s[64:67], s17 offen lds
	ds_read_b128 v[152:155], v228 offset:0x1800
	s_waitcnt lgkmcnt(2)
	v_mfma_f32_16x16x32_bf16 v[110:113], v[156:159], v[132:135], 0
	v_mfma_f32_16x16x32_bf16 v[106:109], v[156:159], v[140:143], 0
	v_mfma_f32_16x16x32_bf16 v[102:105], v[156:159], v[144:147], 0
	v_mfma_f32_16x16x32_bf16 v[98:101], v[156:159], v[148:151], 0
	s_add_i32 m0, s16, 0xc000
	s_nop 0
	buffer_load_dwordx4 v131, s[8:11], s17 offen lds
	ds_read_b128 v[156:159], v228 offset:0x2000
	s_waitcnt lgkmcnt(2)
	v_mfma_f32_16x16x32_bf16 v[94:97], v[160:163], v[132:135], 0
	v_mfma_f32_16x16x32_bf16 v[90:93], v[160:163], v[140:143], 0
	v_mfma_f32_16x16x32_bf16 v[86:89], v[160:163], v[144:147], 0
	v_mfma_f32_16x16x32_bf16 v[82:85], v[160:163], v[148:151], 0
	s_add_i32 m0, s16, 0x6000
	s_nop 0
	buffer_load_dwordx4 v131, s[64:67], s15 offen lds
	ds_read_b128 v[160:163], v228 offset:0x2800
	s_waitcnt lgkmcnt(2)
	v_mfma_f32_16x16x32_bf16 v[78:81], v[152:155], v[132:135], 0
	v_mfma_f32_16x16x32_bf16 v[74:77], v[152:155], v[140:143], 0
	v_mfma_f32_16x16x32_bf16 v[70:73], v[152:155], v[144:147], 0
	v_mfma_f32_16x16x32_bf16 v[66:69], v[152:155], v[148:151], 0
	s_add_i32 m0, s16, 0xe000
	s_nop 0
	buffer_load_dwordx4 v131, s[8:11], s15 offen lds
	ds_read_b128 v[152:155], v228 offset:0x3000
	s_waitcnt lgkmcnt(2)
	v_mfma_f32_16x16x32_bf16 v[62:65], v[156:159], v[132:135], 0
	v_mfma_f32_16x16x32_bf16 v[58:61], v[156:159], v[140:143], 0
	v_mfma_f32_16x16x32_bf16 v[54:57], v[156:159], v[144:147], 0
	v_mfma_f32_16x16x32_bf16 v[50:53], v[156:159], v[148:151], 0
	ds_read_b128 v[156:159], v228 offset:0x3800
	s_waitcnt lgkmcnt(2)
	v_xor_b32_e32 v0, 64, v229
	v_mfma_f32_16x16x32_bf16 v[46:49], v[160:163], v[132:135], 0
	v_mfma_f32_16x16x32_bf16 v[42:45], v[160:163], v[140:143], 0
	v_mfma_f32_16x16x32_bf16 v[38:41], v[160:163], v[144:147], 0
	v_mfma_f32_16x16x32_bf16 v[34:37], v[160:163], v[148:151], 0
	ds_read_b128 v[160:163], v0 offset:0
	ds_read_b128 v[164:167], v0 offset:0x800
	ds_read_b128 v[168:171], v0 offset:0x1000
	s_waitcnt lgkmcnt(4)
	v_mfma_f32_16x16x32_bf16 v[30:33], v[152:155], v[132:135], 0
	v_mfma_f32_16x16x32_bf16 v[26:29], v[152:155], v[140:143], 0
	v_mfma_f32_16x16x32_bf16 v[22:25], v[152:155], v[144:147], 0
	v_mfma_f32_16x16x32_bf16 v[18:21], v[152:155], v[148:151], 0
	ds_read_b128 v[232:235], v0 offset:0x1800
	ds_read_b128 v[172:175], v176 offset:0
	ds_read_b128 v[202:205], v176 offset:0x800
	s_waitcnt lgkmcnt(6)
	v_mfma_f32_16x16x32_bf16 v[14:17], v[156:159], v[132:135], 0
	v_mfma_f32_16x16x32_bf16 v[10:13], v[156:159], v[140:143], 0
	v_mfma_f32_16x16x32_bf16 v[6:9], v[156:159], v[144:147], 0
	v_mfma_f32_16x16x32_bf16 v[2:5], v[156:159], v[148:151], 0
	ds_read_b128 v[132:135], v176 offset:0x1000
	ds_read_b128 v[236:239], v176 offset:0x2800
	s_waitcnt lgkmcnt(3)
	v_mfma_f32_16x16x32_bf16 v[126:129], v[172:175], v[160:163], v[126:129]
	v_mfma_f32_16x16x32_bf16 v[122:125], v[172:175], v[164:167], v[122:125]
	v_mfma_f32_16x16x32_bf16 v[118:121], v[172:175], v[168:171], v[118:121]
	v_mfma_f32_16x16x32_bf16 v[114:117], v[172:175], v[232:235], v[114:117]
	ds_read_b128 v[140:143], v176 offset:0x1800
	ds_read_b128 v[240:243], v176 offset:0x3000
	s_waitcnt lgkmcnt(4)
	v_mfma_f32_16x16x32_bf16 v[110:113], v[202:205], v[160:163], v[110:113]
	v_mfma_f32_16x16x32_bf16 v[106:109], v[202:205], v[164:167], v[106:109]
	v_mfma_f32_16x16x32_bf16 v[102:105], v[202:205], v[168:171], v[102:105]
	v_mfma_f32_16x16x32_bf16 v[98:101], v[202:205], v[232:235], v[98:101]
	ds_read_b128 v[144:147], v176 offset:0x2000
	ds_read_b128 v[244:247], v176 offset:0x3800
	s_waitcnt lgkmcnt(5)
	v_mfma_f32_16x16x32_bf16 v[94:97], v[132:135], v[160:163], v[94:97]
	v_mfma_f32_16x16x32_bf16 v[90:93], v[132:135], v[164:167], v[90:93]
	v_mfma_f32_16x16x32_bf16 v[86:89], v[132:135], v[168:171], v[86:89]
	v_mfma_f32_16x16x32_bf16 v[82:85], v[132:135], v[232:235], v[82:85]
	s_waitcnt lgkmcnt(3)
	v_mfma_f32_16x16x32_bf16 v[78:81], v[140:143], v[160:163], v[78:81]
	v_mfma_f32_16x16x32_bf16 v[74:77], v[140:143], v[164:167], v[74:77]
	v_mfma_f32_16x16x32_bf16 v[70:73], v[140:143], v[168:171], v[70:73]
	v_mfma_f32_16x16x32_bf16 v[66:69], v[140:143], v[232:235], v[66:69]
	s_waitcnt lgkmcnt(1)
	v_mfma_f32_16x16x32_bf16 v[62:65], v[144:147], v[160:163], v[62:65]
	v_mfma_f32_16x16x32_bf16 v[58:61], v[144:147], v[164:167], v[58:61]
	v_mfma_f32_16x16x32_bf16 v[54:57], v[144:147], v[168:171], v[54:57]
	v_mfma_f32_16x16x32_bf16 v[50:53], v[144:147], v[232:235], v[50:53]
	s_setprio 0
	s_waitcnt lgkmcnt(0)
	s_waitcnt vmcnt(0)
	s_add_i32 s13, s13, 0x10000
	s_addk_i32 s15, 0x80
	s_cmp_eq_u32 s15, 0x30400
	s_mov_b32 s2, 0x10000
	s_barrier
	s_cbranch_scc0 .Lrot3_top_l
	s_branch .Lrot3_top_n

.LBB0_269:
	s_lshl_b32 s20, s15, 8
	s_ashr_i32 s19, s18, 31
	s_ashr_i32 s21, s20, 31
	s_lshl_b64 s[8:9], s[18:19], 11
	s_lshl_b64 s[10:11], s[20:21], 11
	s_add_u32 s64, s94, s8
	s_addc_u32 s2, s95, s9
	s_add_u32 s8, s38, s10
	s_waitcnt vmcnt(0)
	s_addc_u32 s9, s39, s11
	s_and_b32 s65, s2, 0xffff
	s_and_b32 s9, s9, 0xffff
	s_mov_b32 s19, 0
	s_mov_b32 s21, 0x60080
	s_waitcnt vmcnt(0)
	s_waitcnt lgkmcnt(0)
	s_barrier
	s_branch .LBB0_271
.LBB0_271:
	s_cmp_eq_u32 s21, 0x60800
	s_mov_b32 s2, 0x10000
	s_and_b32 s2, s19, 0x10000
	s_xor_b32 s10, s2, 0x10000
	s_add_i32 s51, s29, s10
	s_add_i32 s52, s21, 0xfffa0000
	s_add_i32 s53, s51, 0x8000
	s_mov_b32 s10, s66
	s_mov_b32 s11, s67
	s_waitcnt lgkmcnt(0)
	v_add_u32_e32 v228, s2, v205
	v_add_u32_e32 v229, s2, v202
	ds_read_b128 v[130:133], v229 offset:0
	ds_read_b128 v[134:137], v229 offset:0x800
	ds_read_b128 v[138:141], v229 offset:0x1000
	ds_read_b128 v[142:145], v229 offset:0x1800
	ds_read_b128 v[146:149], v228 offset:0
	ds_read_b128 v[150:153], v228 offset:0x800
	s_setprio 1
	s_mov_b32 m0, s51
	s_nop 0
	buffer_load_dwordx4 v173, s[64:67], s52 offen lds
	s_mov_b32 m0, s53
	s_nop 0
	buffer_load_dwordx4 v248, s[8:11], s52 offen lds
	s_add_i32 m0, s51, 0x2000
	s_add_i32 s52, s21, 0xfffc0000
	buffer_load_dwordx4 v173, s[64:67], s52 offen lds
	s_add_i32 m0, s51, 0xa000
	s_nop 0
	buffer_load_dwordx4 v248, s[8:11], s52 offen lds
	ds_read_b128 v[154:157], v228 offset:0x1000
	v_xor_b32_e32 v177, 64, v228
	s_waitcnt lgkmcnt(2)
	v_mfma_f32_16x16x32_bf16 v[122:125], v[146:149], v[130:133], 0
	v_mfma_f32_16x16x32_bf16 v[126:129], v[146:149], v[134:137], 0
	v_mfma_f32_16x16x32_bf16 v[118:121], v[146:149], v[138:141], 0
	v_mfma_f32_16x16x32_bf16 v[114:117], v[146:149], v[142:145], 0
	s_add_i32 m0, s51, 0x4000
	s_add_i32 s52, s21, 0xfffe0000
	buffer_load_dwordx4 v173, s[64:67], s52 offen lds
	ds_read_b128 v[146:149], v228 offset:0x1800
	s_waitcnt lgkmcnt(2)
	v_mfma_f32_16x16x32_bf16 v[110:113], v[150:153], v[130:133], 0
	v_mfma_f32_16x16x32_bf16 v[106:109], v[150:153], v[134:137], 0
	v_mfma_f32_16x16x32_bf16 v[102:105], v[150:153], v[138:141], 0
	v_mfma_f32_16x16x32_bf16 v[98:101], v[150:153], v[142:145], 0
	s_add_i32 m0, s51, 0xc000
	s_nop 0
	buffer_load_dwordx4 v248, s[8:11], s52 offen lds
	ds_read_b128 v[150:153], v228 offset:0x2000
	s_waitcnt lgkmcnt(2)
	v_mfma_f32_16x16x32_bf16 v[94:97], v[154:157], v[130:133], 0
	v_mfma_f32_16x16x32_bf16 v[90:93], v[154:157], v[134:137], 0
	v_mfma_f32_16x16x32_bf16 v[86:89], v[154:157], v[138:141], 0
	v_mfma_f32_16x16x32_bf16 v[82:85], v[154:157], v[142:145], 0
	s_add_i32 m0, s51, 0x6000
	s_nop 0
	buffer_load_dwordx4 v173, s[64:67], s21 offen lds
	ds_read_b128 v[154:157], v228 offset:0x2800
	s_waitcnt lgkmcnt(2)
	v_mfma_f32_16x16x32_bf16 v[78:81], v[146:149], v[130:133], 0
	v_mfma_f32_16x16x32_bf16 v[74:77], v[146:149], v[134:137], 0
	v_mfma_f32_16x16x32_bf16 v[70:73], v[146:149], v[138:141], 0
	v_mfma_f32_16x16x32_bf16 v[66:69], v[146:149], v[142:145], 0
	s_add_i32 m0, s51, 0xe000
	s_nop 0
	buffer_load_dwordx4 v248, s[8:11], s21 offen lds
	ds_read_b128 v[146:149], v228 offset:0x3000
	s_waitcnt lgkmcnt(2)
	v_mfma_f32_16x16x32_bf16 v[62:65], v[150:153], v[130:133], 0
	v_mfma_f32_16x16x32_bf16 v[58:61], v[150:153], v[134:137], 0
	v_mfma_f32_16x16x32_bf16 v[54:57], v[150:153], v[138:141], 0
	v_mfma_f32_16x16x32_bf16 v[50:53], v[150:153], v[142:145], 0
	ds_read_b128 v[150:153], v228 offset:0x3800
	s_waitcnt lgkmcnt(2)
	v_xor_b32_e32 v0, 64, v229
	v_mfma_f32_16x16x32_bf16 v[46:49], v[154:157], v[130:133], 0
	v_mfma_f32_16x16x32_bf16 v[42:45], v[154:157], v[134:137], 0
	v_mfma_f32_16x16x32_bf16 v[38:41], v[154:157], v[138:141], 0
	v_mfma_f32_16x16x32_bf16 v[34:37], v[154:157], v[142:145], 0
	ds_read_b128 v[154:157], v0 offset:0
	ds_read_b128 v[158:161], v0 offset:0x800
	ds_read_b128 v[162:165], v0 offset:0x1000
	s_waitcnt lgkmcnt(4)
	v_mfma_f32_16x16x32_bf16 v[30:33], v[146:149], v[130:133], 0
	v_mfma_f32_16x16x32_bf16 v[26:29], v[146:149], v[134:137], 0
	v_mfma_f32_16x16x32_bf16 v[22:25], v[146:149], v[138:141], 0
	v_mfma_f32_16x16x32_bf16 v[18:21], v[146:149], v[142:145], 0
	ds_read_b128 v[232:235], v0 offset:0x1800
	ds_read_b128 v[166:169], v177 offset:0
	ds_read_b128 v[206:209], v177 offset:0x800
	s_waitcnt lgkmcnt(6)
	v_mfma_f32_16x16x32_bf16 v[14:17], v[150:153], v[130:133], 0
	v_mfma_f32_16x16x32_bf16 v[10:13], v[150:153], v[134:137], 0
	v_mfma_f32_16x16x32_bf16 v[6:9], v[150:153], v[138:141], 0
	v_mfma_f32_16x16x32_bf16 v[2:5], v[150:153], v[142:145], 0
	ds_read_b128 v[130:133], v177 offset:0x1000
	ds_read_b128 v[236:239], v177 offset:0x2800
	s_waitcnt lgkmcnt(3)
	v_mfma_f32_16x16x32_bf16 v[122:125], v[166:169], v[154:157], v[122:125]
	v_mfma_f32_16x16x32_bf16 v[126:129], v[166:169], v[158:161], v[126:129]
	v_mfma_f32_16x16x32_bf16 v[118:121], v[166:169], v[162:165], v[118:121]
	v_mfma_f32_16x16x32_bf16 v[114:117], v[166:169], v[232:235], v[114:117]
	ds_read_b128 v[134:137], v177 offset:0x1800
	ds_read_b128 v[240:243], v177 offset:0x3000
	s_waitcnt lgkmcnt(4)
	v_mfma_f32_16x16x32_bf16 v[110:113], v[206:209], v[154:157], v[110:113]
	v_mfma_f32_16x16x32_bf16 v[106:109], v[206:209], v[158:161], v[106:109]
	v_mfma_f32_16x16x32_bf16 v[102:105], v[206:209], v[162:165], v[102:105]
	v_mfma_f32_16x16x32_bf16 v[98:101], v[206:209], v[232:235], v[98:101]
	ds_read_b128 v[138:141], v177 offset:0x2000
	ds_read_b128 v[244:247], v177 offset:0x3800
	s_waitcnt lgkmcnt(5)
	v_mfma_f32_16x16x32_bf16 v[94:97], v[130:133], v[154:157], v[94:97]
	v_mfma_f32_16x16x32_bf16 v[90:93], v[130:133], v[158:161], v[90:93]
	v_mfma_f32_16x16x32_bf16 v[86:89], v[130:133], v[162:165], v[86:89]
	v_mfma_f32_16x16x32_bf16 v[82:85], v[130:133], v[232:235], v[82:85]
	s_waitcnt lgkmcnt(3)
	v_mfma_f32_16x16x32_bf16 v[78:81], v[134:137], v[154:157], v[78:81]
	v_mfma_f32_16x16x32_bf16 v[74:77], v[134:137], v[158:161], v[74:77]
	v_mfma_f32_16x16x32_bf16 v[70:73], v[134:137], v[162:165], v[70:73]
	v_mfma_f32_16x16x32_bf16 v[66:69], v[134:137], v[232:235], v[66:69]
	s_waitcnt lgkmcnt(1)
	v_mfma_f32_16x16x32_bf16 v[62:65], v[138:141], v[154:157], v[62:65]
	v_mfma_f32_16x16x32_bf16 v[58:61], v[138:141], v[158:161], v[58:61]
	v_mfma_f32_16x16x32_bf16 v[54:57], v[138:141], v[162:165], v[54:57]
	v_mfma_f32_16x16x32_bf16 v[50:53], v[138:141], v[232:235], v[50:53]
	s_setprio 0
	s_waitcnt lgkmcnt(0)
	s_waitcnt vmcnt(0)
	s_add_i32 s19, s19, 0x10000
	s_addk_i32 s21, 0x80
	s_cmp_eq_u32 s21, 0x60800
	s_mov_b32 s2, 0x10000
	s_barrier
	s_cbranch_scc0 .Lrot2_top_l
	s_branch .Lrot2_top_n

.LBB0_294:
	s_ashr_i32 s2, s2, 3
	s_add_i32 s2, s15, s2
	s_ashr_i32 s12, s2, 31
	s_lshr_b32 s12, s12, 28
	s_add_i32 s12, s2, s12
	s_and_b32 s13, s12, 0xfff0
	s_sub_i32 s2, s2, s13
	s_bfe_i32 s13, s2, 0x80000
	s_bfe_u32 s13, s13, 0x2000d
	s_add_i32 s13, s2, s13
	s_bfe_i32 s14, s13, 0x80000
	s_and_b32 s13, s13, 0xfc
	s_sub_i32 s2, s2, s13
	s_sext_i32_i16 s14, s14
	s_sext_i32_i8 s2, s2
	s_lshl_b32 s12, s12, 6
	s_lshl_b32 s20, s2, 8
	s_lshl_b32 s2, s14, 6
	s_and_b32 s12, s12, 0xfffffc00
	s_and_b32 s21, s2, 0xffffff00
	s_add_i32 s20, s20, s12
	s_mul_hi_i32 s13, s21, s22
	s_mul_i32 s12, s21, s22
	s_lshl_b64 s[12:13], s[12:13], 1
	s_add_u32 s12, s96, s12
	s_mul_hi_i32 s15, s20, s22
	s_mul_i32 s14, s20, s22
	s_addc_u32 s2, s97, s13
	s_lshl_b64 s[14:15], s[14:15], 1
	s_waitcnt vmcnt(0)
	s_add_u32 s64, s60, s14
	s_addc_u32 s13, s61, s15
	s_mov_b32 s41, 1
	s_and_b32 s65, s13, 0xffff
	s_and_b32 s13, s2, 0xffff
	s_mov_b32 s44, 0
	s_movk_i32 s45, 0x80
	s_waitcnt vmcnt(0)
	s_waitcnt lgkmcnt(0)
	s_barrier
	s_branch .LBB0_296
.LBB0_296:
	s_and_b32 s2, s44, 0x10000
	s_cmp_ge_u32 s41, s24
	s_xor_b32 s14, s2, 0x10000
	s_add_i32 s46, s26, s14
	s_add_i32 s47, s46, 0x8000
	s_mov_b32 s14, s66
	s_mov_b32 s15, s67
	s_waitcnt lgkmcnt(0)
	v_add_u32_e32 v228, s2, v143
	v_add_u32_e32 v229, s2, v133
	ds_read_b128 v[134:137], v229 offset:0
	ds_read_b128 v[138:141], v229 offset:0x800
	ds_read_b128 v[144:147], v229 offset:0x1000
	ds_read_b128 v[148:151], v229 offset:0x1800
	ds_read_b128 v[152:155], v228 offset:0
	ds_read_b128 v[156:159], v228 offset:0x800
	s_setprio 1
	s_mov_b32 m0, s46
	s_nop 0
	buffer_load_dwordx4 v131, s[64:67], s45 offen lds
	s_mov_b32 m0, s47
	s_add_i32 s47, s27, s45
	buffer_load_dwordx4 v248, s[12:15], s45 offen lds
	s_add_i32 m0, s46, 0x2000
	s_nop 0
	buffer_load_dwordx4 v131, s[64:67], s47 offen lds
	s_add_i32 m0, s46, 0xa000
	s_nop 0
	buffer_load_dwordx4 v248, s[12:15], s47 offen lds
	ds_read_b128 v[160:163], v228 offset:0x1000
	v_xor_b32_e32 v176, 64, v228
	s_waitcnt lgkmcnt(2)
	v_mfma_f32_16x16x32_bf16 v[126:129], v[152:155], v[134:137], 0
	v_mfma_f32_16x16x32_bf16 v[122:125], v[152:155], v[138:141], 0
	v_mfma_f32_16x16x32_bf16 v[118:121], v[152:155], v[144:147], 0
	v_mfma_f32_16x16x32_bf16 v[114:117], v[152:155], v[148:151], 0
	s_add_i32 m0, s46, 0x4000
	s_add_i32 s47, s34, s45
	buffer_load_dwordx4 v131, s[64:67], s47 offen lds
	ds_read_b128 v[152:155], v228 offset:0x1800
	s_waitcnt lgkmcnt(2)
	v_mfma_f32_16x16x32_bf16 v[110:113], v[156:159], v[134:137], 0
	v_mfma_f32_16x16x32_bf16 v[106:109], v[156:159], v[138:141], 0
	v_mfma_f32_16x16x32_bf16 v[102:105], v[156:159], v[144:147], 0
	v_mfma_f32_16x16x32_bf16 v[98:101], v[156:159], v[148:151], 0
	s_add_i32 m0, s46, 0xc000
	s_nop 0
	buffer_load_dwordx4 v248, s[12:15], s47 offen lds
	ds_read_b128 v[156:159], v228 offset:0x2000
	s_waitcnt lgkmcnt(2)
	v_mfma_f32_16x16x32_bf16 v[94:97], v[160:163], v[134:137], 0
	v_mfma_f32_16x16x32_bf16 v[90:93], v[160:163], v[138:141], 0
	v_mfma_f32_16x16x32_bf16 v[86:89], v[160:163], v[144:147], 0
	v_mfma_f32_16x16x32_bf16 v[82:85], v[160:163], v[148:151], 0
	s_add_i32 m0, s46, 0x6000
	s_add_i32 s47, s37, s45
	buffer_load_dwordx4 v131, s[64:67], s47 offen lds
	ds_read_b128 v[160:163], v228 offset:0x2800
	s_waitcnt lgkmcnt(2)
	v_mfma_f32_16x16x32_bf16 v[78:81], v[152:155], v[134:137], 0
	v_mfma_f32_16x16x32_bf16 v[74:77], v[152:155], v[138:141], 0
	v_mfma_f32_16x16x32_bf16 v[70:73], v[152:155], v[144:147], 0
	v_mfma_f32_16x16x32_bf16 v[66:69], v[152:155], v[148:151], 0
	s_add_i32 m0, s46, 0xe000
	s_nop 0
	buffer_load_dwordx4 v248, s[12:15], s47 offen lds
	ds_read_b128 v[152:155], v228 offset:0x3000
	s_waitcnt lgkmcnt(2)
	v_mfma_f32_16x16x32_bf16 v[62:65], v[156:159], v[134:137], 0
	v_mfma_f32_16x16x32_bf16 v[58:61], v[156:159], v[138:141], 0
	v_mfma_f32_16x16x32_bf16 v[54:57], v[156:159], v[144:147], 0
	v_mfma_f32_16x16x32_bf16 v[50:53], v[156:159], v[148:151], 0
	ds_read_b128 v[156:159], v228 offset:0x3800
	s_waitcnt lgkmcnt(2)
	v_xor_b32_e32 v0, 64, v229
	v_mfma_f32_16x16x32_bf16 v[46:49], v[160:163], v[134:137], 0
	v_mfma_f32_16x16x32_bf16 v[42:45], v[160:163], v[138:141], 0
	v_mfma_f32_16x16x32_bf16 v[38:41], v[160:163], v[144:147], 0
	v_mfma_f32_16x16x32_bf16 v[34:37], v[160:163], v[148:151], 0
	ds_read_b128 v[160:163], v0 offset:0
	ds_read_b128 v[164:167], v0 offset:0x800
	ds_read_b128 v[168:171], v0 offset:0x1000
	s_waitcnt lgkmcnt(4)
	v_mfma_f32_16x16x32_bf16 v[30:33], v[152:155], v[134:137], 0
	v_mfma_f32_16x16x32_bf16 v[26:29], v[152:155], v[138:141], 0
	v_mfma_f32_16x16x32_bf16 v[22:25], v[152:155], v[144:147], 0
	v_mfma_f32_16x16x32_bf16 v[18:21], v[152:155], v[148:151], 0
	ds_read_b128 v[232:235], v0 offset:0x1800
	ds_read_b128 v[172:175], v176 offset:0
	ds_read_b128 v[202:205], v176 offset:0x800
	s_waitcnt lgkmcnt(6)
	v_mfma_f32_16x16x32_bf16 v[14:17], v[156:159], v[134:137], 0
	v_mfma_f32_16x16x32_bf16 v[10:13], v[156:159], v[138:141], 0
	v_mfma_f32_16x16x32_bf16 v[6:9], v[156:159], v[144:147], 0
	v_mfma_f32_16x16x32_bf16 v[2:5], v[156:159], v[148:151], 0
	ds_read_b128 v[134:137], v176 offset:0x1000
	ds_read_b128 v[236:239], v176 offset:0x2800
	s_waitcnt lgkmcnt(3)
	v_mfma_f32_16x16x32_bf16 v[126:129], v[172:175], v[160:163], v[126:129]
	v_mfma_f32_16x16x32_bf16 v[122:125], v[172:175], v[164:167], v[122:125]
	v_mfma_f32_16x16x32_bf16 v[118:121], v[172:175], v[168:171], v[118:121]
	v_mfma_f32_16x16x32_bf16 v[114:117], v[172:175], v[232:235], v[114:117]
	ds_read_b128 v[138:141], v176 offset:0x1800
	ds_read_b128 v[240:243], v176 offset:0x3000
	s_waitcnt lgkmcnt(4)
	v_mfma_f32_16x16x32_bf16 v[110:113], v[202:205], v[160:163], v[110:113]
	v_mfma_f32_16x16x32_bf16 v[106:109], v[202:205], v[164:167], v[106:109]
	v_mfma_f32_16x16x32_bf16 v[102:105], v[202:205], v[168:171], v[102:105]
	v_mfma_f32_16x16x32_bf16 v[98:101], v[202:205], v[232:235], v[98:101]
	ds_read_b128 v[144:147], v176 offset:0x2000
	ds_read_b128 v[244:247], v176 offset:0x3800
	s_waitcnt lgkmcnt(5)
	v_mfma_f32_16x16x32_bf16 v[94:97], v[134:137], v[160:163], v[94:97]
	v_mfma_f32_16x16x32_bf16 v[90:93], v[134:137], v[164:167], v[90:93]
	v_mfma_f32_16x16x32_bf16 v[86:89], v[134:137], v[168:171], v[86:89]
	v_mfma_f32_16x16x32_bf16 v[82:85], v[134:137], v[232:235], v[82:85]
	s_waitcnt lgkmcnt(3)
	v_mfma_f32_16x16x32_bf16 v[78:81], v[138:141], v[160:163], v[78:81]
	v_mfma_f32_16x16x32_bf16 v[74:77], v[138:141], v[164:167], v[74:77]
	v_mfma_f32_16x16x32_bf16 v[70:73], v[138:141], v[168:171], v[70:73]
	v_mfma_f32_16x16x32_bf16 v[66:69], v[138:141], v[232:235], v[66:69]
	s_waitcnt lgkmcnt(1)
	v_mfma_f32_16x16x32_bf16 v[62:65], v[144:147], v[160:163], v[62:65]
	v_mfma_f32_16x16x32_bf16 v[58:61], v[144:147], v[164:167], v[58:61]
	v_mfma_f32_16x16x32_bf16 v[54:57], v[144:147], v[168:171], v[54:57]
	v_mfma_f32_16x16x32_bf16 v[50:53], v[144:147], v[232:235], v[50:53]
	s_setprio 0
	s_waitcnt lgkmcnt(0)
	s_waitcnt vmcnt(0)
	s_add_i32 s44, s44, 0x10000
	s_addk_i32 s45, 0x80
	s_add_i32 s41, s41, 1
	s_and_b32 s2, s44, 0x10000
	s_cmp_ge_u32 s41, s24
	s_barrier
	s_cbranch_scc0 .Lrot1_top_l
	s_branch .Lrot1_top_n

.LBB0_427:
	s_bfe_i32 s2, s2, 0x80000
	s_sext_i32_i16 s2, s2
	s_lshr_b32 s2, s2, 2
	s_sext_i32_i8 s2, s2
	s_lshl_b32 s14, s2, 8
	s_ashr_i32 s13, s12, 31
	s_ashr_i32 s15, s14, 31
	s_lshl_b64 s[8:9], s[12:13], 11
	s_lshl_b64 s[10:11], s[14:15], 11
	s_add_u32 s64, s94, s8
	s_addc_u32 s2, s95, s9
	s_add_u32 s8, s18, s10
	s_waitcnt vmcnt(0)
	s_addc_u32 s9, s19, s11
	s_and_b32 s65, s2, 0xffff
	s_and_b32 s9, s9, 0xffff
	s_mov_b32 s13, 0
	s_mov_b32 s15, 0x60080
	s_waitcnt vmcnt(0)
	s_waitcnt lgkmcnt(0)
	s_barrier
	s_branch .LBB0_429
.LBB0_429:
	s_cmp_eq_u32 s15, 0x60800
	s_mov_b32 s2, 0x10000
	s_and_b32 s2, s13, 0x10000
	s_xor_b32 s10, s2, 0x10000
	s_add_i32 s35, s22, s10
	s_add_i32 s36, s15, 0xfffa0000
	s_add_i32 s37, s35, 0x8000
	s_mov_b32 s10, s66
	s_mov_b32 s11, s67
	s_waitcnt lgkmcnt(0)
	v_add_u32_e32 v228, s2, v207
	v_add_u32_e32 v229, s2, v204
	ds_read_b128 v[50:53], v229 offset:0
	ds_read_b128 v[54:57], v229 offset:0x800
	ds_read_b128 v[58:61], v229 offset:0x1000
	ds_read_b128 v[78:81], v229 offset:0x1800
	ds_read_b128 v[98:101], v228 offset:0
	ds_read_b128 v[118:121], v228 offset:0x800
	s_setprio 1
	s_mov_b32 m0, s35
	s_nop 0
	buffer_load_dwordx4 v201, s[64:67], s36 offen lds
	s_mov_b32 m0, s37
	s_nop 0
	buffer_load_dwordx4 v248, s[8:11], s36 offen lds
	s_add_i32 m0, s35, 0x2000
	s_add_i32 s36, s15, 0xfffc0000
	buffer_load_dwordx4 v201, s[64:67], s36 offen lds
	s_add_i32 m0, s35, 0xa000
	s_nop 0
	buffer_load_dwordx4 v248, s[8:11], s36 offen lds
	ds_read_b128 v[138:141], v228 offset:0x1000
	v_xor_b32_e32 v208, 64, v228
	s_waitcnt lgkmcnt(2)
	v_mfma_f32_16x16x32_bf16 v[150:153], v[98:101], v[50:53], 0
	v_mfma_f32_16x16x32_bf16 v[154:157], v[98:101], v[54:57], 0
	v_mfma_f32_16x16x32_bf16 v[142:145], v[98:101], v[58:61], 0
	v_mfma_f32_16x16x32_bf16 v[98:101], v[98:101], v[78:81], 0
	s_add_i32 m0, s35, 0x4000
	s_add_i32 s36, s15, 0xfffe0000
	buffer_load_dwordx4 v201, s[64:67], s36 offen lds
	ds_read_b128 v[146:149], v228 offset:0x1800
	s_waitcnt lgkmcnt(2)
	v_mfma_f32_16x16x32_bf16 v[130:133], v[118:121], v[50:53], 0
	v_mfma_f32_16x16x32_bf16 v[134:137], v[118:121], v[54:57], 0
	v_mfma_f32_16x16x32_bf16 v[122:125], v[118:121], v[58:61], 0
	v_mfma_f32_16x16x32_bf16 v[118:121], v[118:121], v[78:81], 0
	s_add_i32 m0, s35, 0xc000
	s_nop 0
	buffer_load_dwordx4 v248, s[8:11], s36 offen lds
	ds_read_b128 v[126:129], v228 offset:0x2000
	s_waitcnt lgkmcnt(2)
	v_mfma_f32_16x16x32_bf16 v[110:113], v[138:141], v[50:53], 0
	v_mfma_f32_16x16x32_bf16 v[114:117], v[138:141], v[54:57], 0
	v_mfma_f32_16x16x32_bf16 v[102:105], v[138:141], v[58:61], 0
	v_mfma_f32_16x16x32_bf16 v[106:109], v[138:141], v[78:81], 0
	s_add_i32 m0, s35, 0x6000
	s_nop 0
	buffer_load_dwordx4 v201, s[64:67], s15 offen lds
	ds_read_b128 v[138:141], v228 offset:0x2800
	s_waitcnt lgkmcnt(2)
	v_mfma_f32_16x16x32_bf16 v[90:93], v[146:149], v[50:53], 0
	v_mfma_f32_16x16x32_bf16 v[94:97], v[146:149], v[54:57], 0
	v_mfma_f32_16x16x32_bf16 v[82:85], v[146:149], v[58:61], 0
	v_mfma_f32_16x16x32_bf16 v[86:89], v[146:149], v[78:81], 0
	s_add_i32 m0, s35, 0xe000
	s_nop 0
	buffer_load_dwordx4 v248, s[8:11], s15 offen lds
	ds_read_b128 v[146:149], v228 offset:0x3000
	s_waitcnt lgkmcnt(2)
	v_mfma_f32_16x16x32_bf16 v[70:73], v[126:129], v[50:53], 0
	v_mfma_f32_16x16x32_bf16 v[74:77], v[126:129], v[54:57], 0
	v_mfma_f32_16x16x32_bf16 v[62:65], v[126:129], v[58:61], 0
	v_mfma_f32_16x16x32_bf16 v[66:69], v[126:129], v[78:81], 0
	ds_read_b128 v[126:129], v228 offset:0x3800
	s_waitcnt lgkmcnt(2)
	v_xor_b32_e32 v166, 64, v229
	v_mfma_f32_16x16x32_bf16 v[42:45], v[138:141], v[50:53], 0
	v_mfma_f32_16x16x32_bf16 v[46:49], v[138:141], v[54:57], 0
	v_mfma_f32_16x16x32_bf16 v[34:37], v[138:141], v[58:61], 0
	v_mfma_f32_16x16x32_bf16 v[38:41], v[138:141], v[78:81], 0
	ds_read_b128 v[138:141], v166 offset:0
	ds_read_b128 v[158:161], v166 offset:0x800
	ds_read_b128 v[162:165], v166 offset:0x1000
	s_waitcnt lgkmcnt(4)
	v_mfma_f32_16x16x32_bf16 v[26:29], v[146:149], v[50:53], 0
	v_mfma_f32_16x16x32_bf16 v[30:33], v[146:149], v[54:57], 0
	v_mfma_f32_16x16x32_bf16 v[18:21], v[146:149], v[58:61], 0
	v_mfma_f32_16x16x32_bf16 v[22:25], v[146:149], v[78:81], 0
	ds_read_b128 v[166:169], v166 offset:0x1800
	ds_read_b128 v[146:149], v208 offset:0
	ds_read_b128 v[174:177], v208 offset:0x800
	s_waitcnt lgkmcnt(6)
	v_mfma_f32_16x16x32_bf16 v[10:13], v[126:129], v[50:53], 0
	v_mfma_f32_16x16x32_bf16 v[14:17], v[126:129], v[54:57], 0
	v_mfma_f32_16x16x32_bf16 v[2:5], v[126:129], v[58:61], 0
	v_mfma_f32_16x16x32_bf16 v[6:9], v[126:129], v[78:81], 0
	ds_read_b128 v[50:53], v208 offset:0x1000
	ds_read_b128 v[232:235], v208 offset:0x2800
	s_waitcnt lgkmcnt(3)
	v_mfma_f32_16x16x32_bf16 v[150:153], v[146:149], v[138:141], v[150:153]
	v_mfma_f32_16x16x32_bf16 v[154:157], v[146:149], v[158:161], v[154:157]
	v_mfma_f32_16x16x32_bf16 v[142:145], v[146:149], v[162:165], v[142:145]
	v_mfma_f32_16x16x32_bf16 v[146:149], v[146:149], v[166:169], v[98:101]
	ds_read_b128 v[54:57], v208 offset:0x1800
	ds_read_b128 v[236:239], v208 offset:0x3000
	s_waitcnt lgkmcnt(4)
	v_mfma_f32_16x16x32_bf16 v[130:133], v[174:177], v[138:141], v[130:133]
	v_mfma_f32_16x16x32_bf16 v[134:137], v[174:177], v[158:161], v[134:137]
	v_mfma_f32_16x16x32_bf16 v[122:125], v[174:177], v[162:165], v[122:125]
	v_mfma_f32_16x16x32_bf16 v[126:129], v[174:177], v[166:169], v[118:121]
	ds_read_b128 v[58:61], v208 offset:0x2000
	ds_read_b128 v[240:243], v208 offset:0x3800
	s_waitcnt lgkmcnt(5)
	v_mfma_f32_16x16x32_bf16 v[110:113], v[50:53], v[138:141], v[110:113]
	v_mfma_f32_16x16x32_bf16 v[114:117], v[50:53], v[158:161], v[114:117]
	v_mfma_f32_16x16x32_bf16 v[102:105], v[50:53], v[162:165], v[102:105]
	v_mfma_f32_16x16x32_bf16 v[106:109], v[50:53], v[166:169], v[106:109]
	s_waitcnt lgkmcnt(3)
	v_mfma_f32_16x16x32_bf16 v[90:93], v[54:57], v[138:141], v[90:93]
	v_mfma_f32_16x16x32_bf16 v[94:97], v[54:57], v[158:161], v[94:97]
	v_mfma_f32_16x16x32_bf16 v[82:85], v[54:57], v[162:165], v[82:85]
	v_mfma_f32_16x16x32_bf16 v[86:89], v[54:57], v[166:169], v[86:89]
	s_waitcnt lgkmcnt(1)
	v_mfma_f32_16x16x32_bf16 v[70:73], v[58:61], v[138:141], v[70:73]
	v_mfma_f32_16x16x32_bf16 v[74:77], v[58:61], v[158:161], v[74:77]
	v_mfma_f32_16x16x32_bf16 v[62:65], v[58:61], v[162:165], v[62:65]
	v_mfma_f32_16x16x32_bf16 v[66:69], v[58:61], v[166:169], v[66:69]
	s_setprio 0
	s_waitcnt lgkmcnt(0)
	s_waitcnt vmcnt(0)
	s_add_i32 s13, s13, 0x10000
	s_addk_i32 s15, 0x80
	s_cmp_eq_u32 s15, 0x60800
	s_mov_b32 s2, 0x10000
	s_barrier
	s_cbranch_scc0 .Lrot0_top_l
	s_branch .Lrot0_top_n
